# re-pipelined attention loop plus: K-fragment LDS addresses computed before the step barrier, K ring slot shared with the DMA slot computation (16 fewer SALU per iteration), scratch moved off a live co
# speedup vs baseline: 1.0099x; 1.0054x over previous
; #define SBAR() __builtin_amdgcn_sched_barrier(0)
; __device__ __forceinline__ void kload(bf16x8 (&kf)[8], const char* Ks, int r32, int hi, int sb) {
; #pragma unroll
;   for (int d0 = 0; d0 < 4; ++d0) { const int cb = sb + (d0 * 16 + hi * 8) * 2;
;     kf[2 * d0] = *reinterpret_cast<const bf16x8*>(Ks + KSWZ(r32, cb)); kf[2 * d0 + 1] = *reinterpret_cast<const bf16x8*>(Ks + KSWZ(32 + r32, cb)); }
; }
; __device__ __forceinline__ void kmma(f32x16& p0, f32x16& p1, const bf16x8 (&kf)[8], const bf16x8* qr) {
;   asm volatile("s_waitcnt lgkmcnt(0)" ::: "memory"); SBAR();
;   p0 = f32x16{}; p1 = f32x16{};
; #pragma unroll
;   for (int d0 = 0; d0 < 4; ++d0) { p0 = __builtin_amdgcn_mfma_f32_32x32x16_bf16(kf[2 * d0], qr[d0], p0, 0, 0, 0); p1 = __builtin_amdgcn_mfma_f32_32x32x16_bf16(kf[2 * d0 + 1], qr[d0], p1, 0, 0, 0); }
; }
; __device__ __forceinline__ void qkt(f32x16& p0, f32x16& p1, const char* Ks, const bf16x8* qr, int r32, int hi, int sb) {
;   bf16x8 kf[8]; kload(kf, Ks, r32, hi, sb); SBAR(); kmma(p0, p1, kf, qr);
; __device__ __forceinline__ void attn_unit(const bf16* __restrict__ Qb, const bf16* __restrict__ Kh, const bf16* __restrict__ Vh, int klat0, int nlt, int kctx0, int NT,
;                                           float lam, float post, const float* __restrict__ subw, bf16* __restrict__ Ob, char* lds) {
;     ...
;   if (sbr == 0) {
;     asm volatile(".p2align 8" ::: "memory");
;     for (int j = 1; j + 1 < NT; j += 2) {
;       if (j + 2 < NT) DMA_TILE(j + 2);
;       SBAR(); qkt(pB0, pB1, KS(j), qr, r32, hi, sb);
.LBB0_768:
	s_and_b64 vcc, exec, s[0:1]
	s_cbranch_vccz .LBB0_787
	s_cmp_lg_u32 0, -1
	.p2align 8
	s_cselect_b32 s0, 0, 0
	v_mov_b32_e32 v18, v147
	v_mov_b32_e32 v19, v147
	v_mov_b32_e32 v32, v147
	v_mov_b32_e32 v33, v147
	s_add_i32 s31, s0, s31
	v_mov_b32_e32 v20, v147
	v_mov_b32_e32 v21, v147
	v_mov_b32_e32 v22, v147
	v_mov_b32_e32 v23, v147
	v_mov_b32_e32 v24, v147
	v_mov_b32_e32 v25, v147
	v_mov_b32_e32 v26, v147
	v_mov_b32_e32 v27, v147
	v_mov_b32_e32 v28, v147
	v_mov_b32_e32 v29, v147
	v_mov_b32_e32 v30, v147
	v_mov_b32_e32 v31, v147
	v_mov_b64_e32 v[64:65], v[32:33]
	v_mov_b64_e32 v[48:49], v[32:33]
	v_mov_b64_e32 v[2:3], v[18:19]
	s_add_i32 s31, s31, 0xc000
	v_mov_b32_e32 v163, 0
	s_mov_b32 s12, 1
	s_mov_b32 s36, 0x10000
	v_mov_b64_e32 v[62:63], v[30:31]
	v_mov_b64_e32 v[60:61], v[28:29]
	v_mov_b64_e32 v[58:59], v[26:27]
	v_mov_b64_e32 v[56:57], v[24:25]
	v_mov_b64_e32 v[54:55], v[22:23]
	v_mov_b64_e32 v[52:53], v[20:21]
	v_mov_b64_e32 v[50:51], v[18:19]
	v_mov_b64_e32 v[46:47], v[30:31]
	v_mov_b64_e32 v[44:45], v[28:29]
	v_mov_b64_e32 v[42:43], v[26:27]
	v_mov_b64_e32 v[40:41], v[24:25]
	v_mov_b64_e32 v[38:39], v[22:23]
	v_mov_b64_e32 v[36:37], v[20:21]
	v_mov_b64_e32 v[34:35], v[18:19]
	v_mov_b64_e32 v[4:5], v[20:21]
	v_mov_b64_e32 v[6:7], v[22:23]
	v_mov_b64_e32 v[8:9], v[24:25]
	v_mov_b64_e32 v[10:11], v[26:27]
	v_mov_b64_e32 v[12:13], v[28:29]
	v_mov_b64_e32 v[14:15], v[30:31]
	v_mov_b64_e32 v[16:17], v[32:33]
	s_movk_i32 s101, 0x4000
	v_add_u32_e32 v245, s101, v169
	v_add_u32_e32 v246, s101, v170
	v_add_u32_e32 v247, s101, v171
	v_add_u32_e32 v255, s101, v172
	s_mov_b32 s101, 0x8000
.LBB0_770:
	ds_read_b128 v[82:85], v245
	ds_read_b128 v[86:89], v245 offset:8192
	ds_read_b128 v[130:133], v246
	ds_read_b128 v[134:137], v246 offset:8192
	ds_read_b128 v[206:209], v247
	ds_read_b128 v[210:213], v247 offset:8192
	ds_read_b128 v[214:217], v255
	ds_read_b128 v[218:221], v255 offset:8192
	s_and_b32 s13, s36, 0xc000
	v_add_u32_e32 v244, s13, v164
	ds_read_b64_tr_b16 v[228:229], v244 offset:0
	ds_read_b64_tr_b16 v[230:231], v244 offset:0x800
	ds_read_b64_tr_b16 v[232:233], v244 offset:0x1000
	ds_read_b64_tr_b16 v[234:235], v244 offset:0x1800
	ds_read_b64_tr_b16 v[236:237], v244 offset:0x2000
	ds_read_b64_tr_b16 v[238:239], v244 offset:0x2800
	ds_read_b64_tr_b16 v[240:241], v244 offset:0x3000
	ds_read_b64_tr_b16 v[242:243], v244 offset:0x3800
	v_exp_f32_e32 v148, v66
	v_add_f32_e32 v66, 0, v175
	v_add_f32_e32 v66, v177, v66
	v_add_f32_e32 v66, v192, v66
	v_add_f32_e32 v66, v195, v66
	v_add_f32_e32 v66, v196, v66
	v_add_f32_e32 v66, v199, v66
	v_add_f32_e32 v66, v200, v66
	v_add_f32_e32 v66, v203, v66
	v_add_f32_e32 v66, v176, v66
	v_add_f32_e32 v66, v193, v66
	v_add_f32_e32 v66, v194, v66
	v_add_f32_e32 v66, v197, v66
	v_add_f32_e32 v66, v198, v66
	v_exp_f32_e32 v149, v67
	v_add_f32_e32 v66, v201, v66
	s_waitcnt lgkmcnt(15)
	v_mfma_f32_32x32x16_bf16 v[98:113], v[82:85], v[126:129], 0
	v_exp_f32_e32 v150, v68
	s_add_i32 s37, s12, 2
	v_add_f32_e32 v66, v202, v66
	s_cmpk_lt_u32 s12, 0x7e
	v_exp_f32_e32 v151, v69
	s_cselect_b64 s[0:1], -1, 0
	v_add_f32_e32 v66, v204, v66
	s_and_b64 s[10:11], s[0:1], exec
	s_cselect_b32 s10, 0, 0xffffff80
	s_waitcnt lgkmcnt(14)
	v_mfma_f32_32x32x16_bf16 v[82:97], v[86:89], v[126:129], 0
	v_exp_f32_e32 v186, v70
	s_add_i32 s58, s37, s10
	v_add_f32_e32 v66, v148, v66
	s_and_b64 s[0:1], s[0:1], exec
	v_exp_f32_e32 v187, v71
	s_cselect_b32 s1, s9, s30
	v_add_f32_e32 v66, v149, v66
	s_cselect_b32 s0, s8, s26
	v_exp_f32_e32 v188, v72
	s_lshl_b64 s[10:11], s[58:59], 17
	s_lshl_b64 s[0:1], s[0:1], 11
	s_waitcnt lgkmcnt(13)
	v_mfma_f32_32x32x16_bf16 v[98:113], v[130:133], v[122:125], v[98:113]
	v_add_f32_e32 v66, v150, v66
	s_add_u32 s10, s10, s0
	v_exp_f32_e32 v189, v73
	s_addc_u32 s11, s11, s1
	v_add_f32_e32 v66, v151, v66
	s_add_u32 s0, s20, s10
	v_exp_f32_e32 v205, v74
	s_addc_u32 s1, s21, s11
	s_add_u32 s10, s22, s10
	s_waitcnt lgkmcnt(12)
	v_mfma_f32_32x32x16_bf16 v[82:97], v[134:137], v[122:125], v[82:97]
	v_add_f32_e32 v66, v186, v66
	s_addc_u32 s11, s23, s11
	v_exp_f32_e32 v222, v75
	s_and_b32 s13, s37, 0xff
	v_add_f32_e32 v66, v187, v66
	s_mulk_i32 s13, 0xab
	v_exp_f32_e32 v223, v76
	s_lshr_b32 s13, s13, 9
	v_add_f32_e32 v66, v188, v66
	s_mul_i32 s13, s13, 3
	s_sub_i32 s13, s37, s13
	s_waitcnt lgkmcnt(11)
	v_mfma_f32_32x32x16_bf16 v[98:113], v[206:209], v[118:121], v[98:113]
	v_exp_f32_e32 v224, v77
	s_and_b32 s13, s13, 0xff
	v_add_f32_e32 v66, v189, v66
	s_lshl_b32 s13, s13, 14
	s_mov_b32 s100, s13
	v_exp_f32_e32 v225, v78
	s_add_i32 s42, s36, 0xffffc000
	v_add_f32_e32 v66, v205, v66
	s_and_b32 s42, s42, 0xc000
	s_add_i32 s13, s13, s27
	s_waitcnt lgkmcnt(10)
	v_mfma_f32_32x32x16_bf16 v[82:97], v[210:213], v[118:121], v[82:97]
	v_exp_f32_e32 v226, v79
	s_add_i32 s42, s42, s31
	v_add_f32_e32 v66, v222, v66
	v_lshl_add_u64 v[246:247], s[0:1], 0, v[146:147]
	v_exp_f32_e32 v227, v80
	s_mov_b32 m0, s13
	v_add_f32_e32 v66, v223, v66
	s_nop 0
	v_exp_f32_e32 v81, v81
	global_load_lds_dwordx4 v[246:247], off
	v_lshl_add_u64 v[246:247], s[10:11], 0, v[142:143]
	s_waitcnt lgkmcnt(9)
	v_mfma_f32_32x32x16_bf16 v[98:113], v[214:217], v[114:117], v[98:113]
	v_add_f32_e32 v66, v224, v66
	s_mov_b32 m0, s42
	v_add_f32_e32 v66, v225, v66
	s_nop 0
	v_add_f32_e32 v66, v226, v66
	global_load_lds_dwordx4 v[246:247], off
	v_add_f32_e32 v66, v227, v66
	v_lshl_add_u64 v[246:247], s[0:1], 0, v[144:145]
	s_add_i32 m0, s13, 0x2000
	s_waitcnt lgkmcnt(8)
; __device__ __forceinline__ void partialSM(f32x16& p0, f32x16& p1, float& m_reg, float& mn, float& alpha) {
;   constexpr float C = SCALE * 1.4426950408889634f;
;   float pmax = p0[0]; for (int r = 1; r < 16; ++r) pmax = fmaxf(pmax, p0[r]); for (int r = 0; r < 16; ++r) pmax = fmaxf(pmax, p1[r]);
;   { auto rr = __builtin_amdgcn_permlane32_swap(__float_as_uint(pmax), __float_as_uint(pmax), false, false);
;     pmax = fmaxf(__uint_as_float(rr[0]), __uint_as_float(rr[1])); }
;   if (__builtin_expect(__all(pmax - m_reg <= THR / SCALE), 1)) { mn = m_reg; alpha = 1.f; }
;   else { mn = fmaxf(m_reg, pmax); alpha = __builtin_amdgcn_exp2f((m_reg - mn) * C); m_reg = mn; }
;   float mnC = -mn * C;
;   for (int r = 0; r < 16; ++r) p0[r] = fmaf(p0[r], C, mnC); for (int r = 0; r < 16; ++r) p1[r] = fmaf(p1[r], C, mnC);
;   for (int r = 0; r < 16; ++r) p0[r] = __builtin_amdgcn_exp2f(p0[r]);
; }
; __device__ __forceinline__ void finishSM(f32x16& p0, f32x16& p1, float alpha, float& l_reg, bf16x8& pa0, bf16x8& pa1, bf16x8& pa2, bf16x8& pa3) {
;   for (int r = 0; r < 16; ++r) p1[r] = __builtin_amdgcn_exp2f(p1[r]);
;   float ps = 0; for (int r = 0; r < 16; ++r) ps += p0[r]; for (int r = 0; r < 16; ++r) ps += p1[r];
;   { auto rr = __builtin_amdgcn_permlane32_swap(__float_as_uint(ps), __float_as_uint(ps), false, false);
;     ps = __uint_as_float(rr[0]) + __uint_as_float(rr[1]); }
;   l_reg = l_reg * alpha + ps;
;     ...
;   PK4(p0, 0, pa0); PK4(p0, 8, pa1); PK4(p1, 0, pa2); PK4(p1, 8, pa3);
;     ...
; }
; template <int D0> __device__ __forceinline__ void v_frag_read(VFrag& f, int vb) {
;   f.l0 = tr_read<v_rd_off(D0, 0, 0)>(vb); f.h0 = tr_read<v_rd_off(D0, 0, 1)>(vb); f.l1 = tr_read<v_rd_off(D0, 1, 0)>(vb); f.h1 = tr_read<v_rd_off(D0, 1, 1)>(vb);
;   f.l2 = tr_read<v_rd_off(D0, 2, 0)>(vb); f.h2 = tr_read<v_rd_off(D0, 2, 1)>(vb); f.l3 = tr_read<v_rd_off(D0, 3, 0)>(vb); f.h3 = tr_read<v_rd_off(D0, 3, 1)>(vb);
; }
; __device__ __forceinline__ void pv_mma(f32x16& od, const VFrag& f, bf16x8 pa0, bf16x8 pa1, bf16x8 pa2, bf16x8 pa3) {
;     ...
;   od = __builtin_amdgcn_mfma_f32_32x32x16_bf16(pa0, PK(f.l0, f.h0), od, 0, 0, 0);
;   od = __builtin_amdgcn_mfma_f32_32x32x16_bf16(pa1, PK(f.l1, f.h1), od, 0, 0, 0);
;   od = __builtin_amdgcn_mfma_f32_32x32x16_bf16(pa2, PK(f.l2, f.h2), od, 0, 0, 0);
;   od = __builtin_amdgcn_mfma_f32_32x32x16_bf16(pa3, PK(f.l3, f.h3), od, 0, 0, 0);
;     ...
; }
	v_mfma_f32_32x32x16_bf16 v[82:97], v[218:221], v[114:117], v[82:97]
	v_add_f32_e32 v130, v81, v66
	s_nop 0
	v_mov_b32_e32 v131, v130
	global_load_lds_dwordx4 v[246:247], off
	v_cvt_pk_bf16_f32 v66, v175, v177
	v_lshl_add_u64 v[246:247], s[10:11], 0, v[154:155]
	v_cvt_pk_bf16_f32 v67, v192, v195
	s_add_i32 m0, s42, 0x2000
	v_cvt_pk_bf16_f32 v68, v196, v199
	s_nop 0
	global_load_lds_dwordx4 v[246:247], off
	v_permlane32_swap_b32_e32 v130, v131
	v_cvt_pk_bf16_f32 v69, v200, v203
	v_permlane32_swap_b32_e32 v66, v68
	v_cvt_pk_bf16_f32 v70, v176, v193
	v_cvt_pk_bf16_f32 v71, v194, v197
	v_cvt_pk_bf16_f32 v72, v198, v201
	v_cvt_pk_bf16_f32 v73, v202, v204
	v_cvt_pk_bf16_f32 v74, v148, v149
	v_cvt_pk_bf16_f32 v75, v150, v151
	v_cvt_pk_bf16_f32 v76, v186, v187
	v_cvt_pk_bf16_f32 v77, v188, v189
	v_cvt_pk_bf16_f32 v78, v205, v222
	v_cvt_pk_bf16_f32 v79, v223, v224
	v_cvt_pk_bf16_f32 v80, v225, v226
	v_cvt_pk_bf16_f32 v81, v227, v81
	v_permlane32_swap_b32_e32 v67, v69
	v_permlane32_swap_b32_e32 v70, v72
	v_permlane32_swap_b32_e32 v71, v73
	v_permlane32_swap_b32_e32 v74, v76
	v_permlane32_swap_b32_e32 v75, v77
	v_permlane32_swap_b32_e32 v78, v80
	v_permlane32_swap_b32_e32 v79, v81
	ds_read_b64_tr_b16 v[204:205], v244 offset:0x200
	ds_read_b64_tr_b16 v[206:207], v244 offset:0xa00
	ds_read_b64_tr_b16 v[208:209], v244 offset:0x1200
	ds_read_b64_tr_b16 v[210:211], v244 offset:0x1a00
	ds_read_b64_tr_b16 v[212:213], v244 offset:0x2200
	ds_read_b64_tr_b16 v[214:215], v244 offset:0x2a00
	ds_read_b64_tr_b16 v[216:217], v244 offset:0x3200
	ds_read_b64_tr_b16 v[218:219], v244 offset:0x3a00
	s_waitcnt lgkmcnt(14)
	v_mfma_f32_32x32x16_bf16 v[18:33], v[66:69], v[228:231], v[18:33]
	v_max_f32_e32 v245, v99, v99
	v_max_f32_e32 v246, v98, v98
	v_max_f32_e32 v245, v246, v245
	v_max3_f32 v245, v245, v100, v101
	v_max3_f32 v245, v245, v102, v103
	v_max3_f32 v245, v245, v104, v105
	v_max3_f32 v245, v245, v106, v107
	v_max3_f32 v245, v245, v108, v109
	s_waitcnt lgkmcnt(12)
	v_mfma_f32_32x32x16_bf16 v[18:33], v[70:73], v[232:235], v[18:33]
	v_max3_f32 v245, v245, v110, v111
	v_max3_f32 v245, v245, v112, v113
	v_max3_f32 v245, v245, v82, v83
	v_max3_f32 v245, v245, v84, v85
	v_max3_f32 v245, v245, v86, v87
	v_max3_f32 v245, v245, v88, v89
	v_max3_f32 v245, v245, v90, v91
	v_max3_f32 v245, v245, v92, v93
	s_waitcnt lgkmcnt(10)
	v_mfma_f32_32x32x16_bf16 v[18:33], v[74:77], v[236:239], v[18:33]
	v_max3_f32 v245, v245, v94, v95
	v_max3_f32 v245, v245, v96, v97
	v_mov_b32_e32 v246, v245
	s_nop 1
	v_permlane32_swap_b32_e32 v245, v246
	v_max_f32_e32 v246, v246, v246
	v_max_f32_e32 v245, v245, v245
	v_max_f32_e32 v245, v245, v246
	v_sub_f32_e32 v246, v245, v174
	s_waitcnt lgkmcnt(8)
	v_mfma_f32_32x32x16_bf16 v[18:33], v[78:81], v[240:243], v[18:33]
	v_cmp_ge_f32_e32 vcc, s63, v246
	v_max_f32_e32 v246, v174, v174
	v_max_f32_e32 v245, v246, v245
	v_sub_f32_e32 v246, v174, v245
	v_mul_f32_e32 v246, 0x3e38aa3b, v246
	v_exp_f32_e32 v246, v246
	s_cmp_eq_u64 vcc, exec
	s_cselect_b64 s[0:1], -1, 0
	v_cndmask_b32_e64 v132, v246, 1.0, s[0:1]
	ds_read_b64_tr_b16 v[228:229], v244 offset:0x400
	ds_read_b64_tr_b16 v[230:231], v244 offset:0xc00
	ds_read_b64_tr_b16 v[232:233], v244 offset:0x1400
	ds_read_b64_tr_b16 v[234:235], v244 offset:0x1c00
	ds_read_b64_tr_b16 v[236:237], v244 offset:0x2400
	ds_read_b64_tr_b16 v[238:239], v244 offset:0x2c00
	ds_read_b64_tr_b16 v[240:241], v244 offset:0x3400
	ds_read_b64_tr_b16 v[242:243], v244 offset:0x3c00
	v_cndmask_b32_e64 v133, v245, v174, s[0:1]
	v_mul_f32_e32 v148, 0xbe38aa3b, v133
	s_waitcnt lgkmcnt(14)
	v_mfma_f32_32x32x16_bf16 v[50:65], v[66:69], v[204:207], v[50:65]
	v_fmamk_f32 v98, v98, 0x3e38aa3b, v148
	v_fmamk_f32 v99, v99, 0x3e38aa3b, v148
	v_fmamk_f32 v100, v100, 0x3e38aa3b, v148
	v_fmamk_f32 v101, v101, 0x3e38aa3b, v148
	s_waitcnt lgkmcnt(12)
	v_mfma_f32_32x32x16_bf16 v[50:65], v[70:73], v[208:211], v[50:65]
	v_fmamk_f32 v102, v102, 0x3e38aa3b, v148
	v_fmamk_f32 v103, v103, 0x3e38aa3b, v148
	v_fmamk_f32 v104, v104, 0x3e38aa3b, v148
	v_fmamk_f32 v105, v105, 0x3e38aa3b, v148
	s_waitcnt lgkmcnt(10)
	v_mfma_f32_32x32x16_bf16 v[50:65], v[74:77], v[212:215], v[50:65]
	v_fmamk_f32 v106, v106, 0x3e38aa3b, v148
	v_fmamk_f32 v107, v107, 0x3e38aa3b, v148
	v_fmamk_f32 v108, v108, 0x3e38aa3b, v148
	v_fmamk_f32 v109, v109, 0x3e38aa3b, v148
	s_waitcnt lgkmcnt(8)
	v_mfma_f32_32x32x16_bf16 v[50:65], v[78:81], v[216:219], v[50:65]
	v_fmamk_f32 v110, v110, 0x3e38aa3b, v148
	v_fmamk_f32 v111, v111, 0x3e38aa3b, v148
	v_fmamk_f32 v112, v112, 0x3e38aa3b, v148
	v_fmamk_f32 v113, v113, 0x3e38aa3b, v148
	ds_read_b64_tr_b16 v[204:205], v244 offset:0x600
	ds_read_b64_tr_b16 v[206:207], v244 offset:0xe00
	ds_read_b64_tr_b16 v[208:209], v244 offset:0x1600
	ds_read_b64_tr_b16 v[210:211], v244 offset:0x1e00
	ds_read_b64_tr_b16 v[212:213], v244 offset:0x2600
	ds_read_b64_tr_b16 v[214:215], v244 offset:0x2e00
	ds_read_b64_tr_b16 v[216:217], v244 offset:0x3600
	ds_read_b64_tr_b16 v[218:219], v244 offset:0x3e00
	s_waitcnt lgkmcnt(14)
	v_mfma_f32_32x32x16_bf16 v[34:49], v[66:69], v[228:231], v[34:49]
	v_fmamk_f32 v82, v82, 0x3e38aa3b, v148
	v_fmamk_f32 v83, v83, 0x3e38aa3b, v148
	v_fmamk_f32 v84, v84, 0x3e38aa3b, v148
	v_fmamk_f32 v85, v85, 0x3e38aa3b, v148
	s_waitcnt lgkmcnt(12)
	v_mfma_f32_32x32x16_bf16 v[34:49], v[70:73], v[232:235], v[34:49]
	v_fmamk_f32 v86, v86, 0x3e38aa3b, v148
	v_fmamk_f32 v87, v87, 0x3e38aa3b, v148
	s_add_i32 s13, s36, 0xffff4000
	v_fmamk_f32 v149, v88, 0x3e38aa3b, v148
	s_waitcnt lgkmcnt(10)
	v_mfma_f32_32x32x16_bf16 v[34:49], v[74:77], v[236:239], v[34:49]
	v_fmamk_f32 v150, v89, 0x3e38aa3b, v148
	v_fmamk_f32 v151, v90, 0x3e38aa3b, v148
	v_fmamk_f32 v186, v91, 0x3e38aa3b, v148
	v_fmamk_f32 v187, v92, 0x3e38aa3b, v148
	s_waitcnt lgkmcnt(8)
	v_mfma_f32_32x32x16_bf16 v[34:49], v[78:81], v[240:243], v[34:49]
	v_fmamk_f32 v188, v93, 0x3e38aa3b, v148
	v_fmamk_f32 v189, v94, 0x3e38aa3b, v148
	v_exp_f32_e32 v192, v98
	v_exp_f32_e32 v193, v99
	v_exp_f32_e32 v194, v100
	v_exp_f32_e32 v195, v101
	s_waitcnt lgkmcnt(6)
	v_mfma_f32_32x32x16_bf16 v[2:17], v[66:69], v[204:207], v[2:17]
	v_exp_f32_e32 v196, v102
	v_exp_f32_e32 v197, v103
	v_exp_f32_e32 v198, v104
	v_exp_f32_e32 v199, v105
	s_waitcnt lgkmcnt(4)
	v_mfma_f32_32x32x16_bf16 v[2:17], v[70:73], v[208:211], v[2:17]
	v_exp_f32_e32 v200, v106
	v_exp_f32_e32 v201, v107
	v_exp_f32_e32 v202, v108
	v_exp_f32_e32 v203, v109
	v_exp_f32_e32 v204, v110
	v_exp_f32_e32 v205, v111
	s_waitcnt lgkmcnt(2)
	v_mfma_f32_32x32x16_bf16 v[2:17], v[74:77], v[212:215], v[2:17]
	v_exp_f32_e32 v206, v112
	v_exp_f32_e32 v207, v113
	v_fmamk_f32 v208, v95, 0x3e38aa3b, v148
	v_fmamk_f32 v209, v96, 0x3e38aa3b, v148
	v_fmac_f32_e32 v148, 0x3e38aa3b, v97
	s_waitcnt lgkmcnt(0)
	v_mfma_f32_32x32x16_bf16 v[2:17], v[78:81], v[216:219], v[2:17]
	v_add_u32_e32 v245, s101, v169
	v_add_u32_e32 v246, s101, v170
	v_add_u32_e32 v247, s101, v171
	v_add_u32_e32 v255, s101, v172
	v_cmp_gt_f32_e32 vcc, 1.0, v132
	s_cbranch_vccz .LBB0_774
; #define SBAR() __builtin_amdgcn_sched_barrier(0)
; __device__ __forceinline__ void finishSM(f32x16& p0, f32x16& p1, float alpha, float& l_reg, bf16x8& pa0, bf16x8& pa1, bf16x8& pa2, bf16x8& pa3) {
;   for (int r = 0; r < 16; ++r) p1[r] = __builtin_amdgcn_exp2f(p1[r]);
;   float ps = 0; for (int r = 0; r < 16; ++r) ps += p0[r]; for (int r = 0; r < 16; ++r) ps += p1[r];
;   { auto rr = __builtin_amdgcn_permlane32_swap(__float_as_uint(ps), __float_as_uint(ps), false, false);
;     ps = __uint_as_float(rr[0]) + __uint_as_float(rr[1]); }
;   l_reg = l_reg * alpha + ps;
;     ...
;   PK4(p0, 0, pa0); PK4(p0, 8, pa1); PK4(p1, 0, pa2); PK4(p1, 8, pa3);
;     ...
; }
; __device__ __forceinline__ void kload(bf16x8 (&kf)[8], const char* Ks, int r32, int hi, int sb) {
; #pragma unroll
;   for (int d0 = 0; d0 < 4; ++d0) { const int cb = sb + (d0 * 16 + hi * 8) * 2;
;     kf[2 * d0] = *reinterpret_cast<const bf16x8*>(Ks + KSWZ(r32, cb)); kf[2 * d0 + 1] = *reinterpret_cast<const bf16x8*>(Ks + KSWZ(32 + r32, cb)); }
; }
; __device__ __forceinline__ void kmma(f32x16& p0, f32x16& p1, const bf16x8 (&kf)[8], const bf16x8* qr) {
;   asm volatile("s_waitcnt lgkmcnt(0)" ::: "memory"); SBAR();
;   p0 = f32x16{}; p1 = f32x16{};
; #pragma unroll
;   for (int d0 = 0; d0 < 4; ++d0) { p0 = __builtin_amdgcn_mfma_f32_32x32x16_bf16(kf[2 * d0], qr[d0], p0, 0, 0, 0); p1 = __builtin_amdgcn_mfma_f32_32x32x16_bf16(kf[2 * d0 + 1], qr[d0], p1, 0, 0, 0); }
; }
; __device__ __forceinline__ void qkt(f32x16& p0, f32x16& p1, const char* Ks, const bf16x8* qr, int r32, int hi, int sb) {
;   bf16x8 kf[8]; kload(kf, Ks, r32, hi, sb); SBAR(); kmma(p0, p1, kf, qr);
; }
	s_and_saveexec_b64 s[10:11], s[40:41]
	ds_write_b32 v162, v132 offset:128
	s_or_b64 exec, exec, s[10:11]
	s_waitcnt lgkmcnt(0)
	v_add_u32_e32 v67, s18, v140
	ds_read_b128 v[68:71], v67 offset:224
	ds_read_b128 v[72:75], v67 offset:192
	ds_read_b128 v[76:79], v67 offset:160
	ds_read_b128 v[134:137], v67 offset:128
	s_waitcnt lgkmcnt(0)
	v_pk_mul_f32 v[30:31], v[30:31], v[68:69]
	v_pk_mul_f32 v[26:27], v[26:27], v[72:73]
	v_pk_mul_f32 v[22:23], v[22:23], v[76:77]
	v_pk_mul_f32 v[32:33], v[32:33], v[70:71]
	v_pk_mul_f32 v[28:29], v[28:29], v[74:75]
	v_pk_mul_f32 v[24:25], v[24:25], v[78:79]
	v_pk_mul_f32 v[20:21], v[20:21], v[136:137]
	v_pk_mul_f32 v[18:19], v[18:19], v[134:135]
	v_pk_mul_f32 v[62:63], v[62:63], v[68:69]
	v_pk_mul_f32 v[58:59], v[58:59], v[72:73]
	v_pk_mul_f32 v[54:55], v[54:55], v[76:77]
	v_pk_mul_f32 v[64:65], v[64:65], v[70:71]
	v_pk_mul_f32 v[60:61], v[60:61], v[74:75]
	v_pk_mul_f32 v[56:57], v[56:57], v[78:79]
	v_pk_mul_f32 v[52:53], v[52:53], v[136:137]
	v_pk_mul_f32 v[50:51], v[50:51], v[134:135]
	v_pk_mul_f32 v[46:47], v[46:47], v[68:69]
	v_pk_mul_f32 v[42:43], v[42:43], v[72:73]
	v_pk_mul_f32 v[38:39], v[38:39], v[76:77]
	v_pk_mul_f32 v[48:49], v[48:49], v[70:71]
	v_pk_mul_f32 v[44:45], v[44:45], v[74:75]
	v_pk_mul_f32 v[40:41], v[40:41], v[78:79]
	v_pk_mul_f32 v[36:37], v[36:37], v[136:137]
	v_pk_mul_f32 v[34:35], v[34:35], v[134:135]
	v_pk_mul_f32 v[14:15], v[14:15], v[68:69]
	v_pk_mul_f32 v[10:11], v[10:11], v[72:73]
	v_pk_mul_f32 v[6:7], v[6:7], v[76:77]
	v_pk_mul_f32 v[16:17], v[16:17], v[70:71]
	v_pk_mul_f32 v[12:13], v[12:13], v[74:75]
	v_pk_mul_f32 v[8:9], v[8:9], v[78:79]
	v_pk_mul_f32 v[4:5], v[4:5], v[136:137]
	v_pk_mul_f32 v[2:3], v[2:3], v[134:135]
.LBB0_774:
	s_waitcnt vmcnt(4)
	s_barrier
	s_and_b32 s46, s13, 0xc000
	v_add_u32_e32 v244, s46, v164
	ds_read_b128 v[66:69], v245
	ds_read_b128 v[70:73], v245 offset:8192
	ds_read_b128 v[98:101], v246
	ds_read_b128 v[102:105], v246 offset:8192
	ds_read_b128 v[106:109], v247
	ds_read_b128 v[110:113], v247 offset:8192
	ds_read_b128 v[134:137], v255
	ds_read_b128 v[174:177], v255 offset:8192
	ds_read_b64_tr_b16 v[228:229], v244 offset:0
	ds_read_b64_tr_b16 v[230:231], v244 offset:0x800
	ds_read_b64_tr_b16 v[232:233], v244 offset:0x1000
	ds_read_b64_tr_b16 v[234:235], v244 offset:0x1800
	ds_read_b64_tr_b16 v[236:237], v244 offset:0x2000
	ds_read_b64_tr_b16 v[238:239], v244 offset:0x2800
	ds_read_b64_tr_b16 v[240:241], v244 offset:0x3000
	ds_read_b64_tr_b16 v[242:243], v244 offset:0x3800
	v_exp_f32_e32 v210, v82
	v_exp_f32_e32 v211, v83
	v_exp_f32_e32 v212, v84
	v_exp_f32_e32 v213, v85
	v_exp_f32_e32 v214, v86
	v_exp_f32_e32 v215, v87
	v_add_f32_e32 v216, 0, v192
	v_add_f32_e32 v216, v193, v216
	v_add_f32_e32 v216, v194, v216
	v_add_f32_e32 v216, v195, v216
	v_exp_f32_e32 v149, v149
	v_exp_f32_e32 v150, v150
	v_exp_f32_e32 v151, v151
	v_exp_f32_e32 v186, v186
	v_exp_f32_e32 v187, v187
	v_exp_f32_e32 v188, v188
	s_waitcnt lgkmcnt(15)
	v_mfma_f32_32x32x16_bf16 v[82:97], v[66:69], v[126:129], 0
	v_exp_f32_e32 v189, v189
	s_add_i32 s46, s12, 3
	v_exp_f32_e32 v208, v208
	s_cmpk_lt_u32 s12, 0x7d
	v_exp_f32_e32 v209, v209
	s_cselect_b64 s[42:43], -1, 0
	v_exp_f32_e32 v148, v148
	s_waitcnt lgkmcnt(14)
	v_mfma_f32_32x32x16_bf16 v[66:81], v[70:73], v[126:129], 0
	v_add_f32_e32 v255, v196, v216
	s_and_b64 s[44:45], s[42:43], exec
	v_add_f32_e32 v255, v197, v255
	s_cselect_b32 s44, 0, 0xffffff80
	v_add_f32_e32 v255, v198, v255
	s_add_i32 s58, s46, s44
	v_add_f32_e32 v255, v199, v255
	s_and_b64 s[42:43], s[42:43], exec
	v_add_f32_e32 v255, v200, v255
	s_waitcnt lgkmcnt(13)
	v_mfma_f32_32x32x16_bf16 v[82:97], v[98:101], v[122:125], v[82:97]
	v_add_f32_e32 v255, v201, v255
	s_cselect_b32 s43, s9, s30
	v_add_f32_e32 v255, v202, v255
	s_cselect_b32 s42, s8, s26
	v_add_f32_e32 v255, v203, v255
	s_lshl_b64 s[44:45], s[58:59], 17
	v_add_f32_e32 v255, v204, v255
	s_lshl_b64 s[42:43], s[42:43], 11
	s_waitcnt lgkmcnt(12)
	v_mfma_f32_32x32x16_bf16 v[66:81], v[102:105], v[122:125], v[66:81]
	v_add_f32_e32 v255, v205, v255
	s_add_u32 s44, s44, s42
	v_add_f32_e32 v255, v206, v255
	s_addc_u32 s45, s45, s43
	v_add_f32_e32 v255, v207, v255
	s_add_u32 s42, s20, s44
	v_add_f32_e32 v255, v210, v255
	v_add_f32_e32 v255, v211, v255
	s_waitcnt lgkmcnt(11)
	v_mfma_f32_32x32x16_bf16 v[82:97], v[106:109], v[118:121], v[82:97]
	v_add_f32_e32 v255, v212, v255
	s_addc_u32 s43, s21, s45
	v_add_f32_e32 v255, v213, v255
	s_add_u32 s44, s22, s44
	v_add_f32_e32 v255, v214, v255
	s_mul_i32 s47, s46, 0xab
	v_add_f32_e32 v255, v215, v255
	s_addc_u32 s45, s23, s45
	s_waitcnt lgkmcnt(10)
	v_mfma_f32_32x32x16_bf16 v[66:81], v[110:113], v[118:121], v[66:81]
	v_add_f32_e32 v255, v149, v255
	s_bfe_u32 s47, s47, 0x70009
	v_add_f32_e32 v255, v150, v255
	s_mul_i32 s47, s47, 3
	v_add_f32_e32 v255, v151, v255
	s_sub_i32 s46, s46, s47
	v_add_f32_e32 v255, v186, v255
	s_and_b32 s46, s46, 0xff
	v_add_f32_e32 v255, v187, v255
	s_waitcnt lgkmcnt(9)
	v_mfma_f32_32x32x16_bf16 v[82:97], v[134:137], v[114:117], v[82:97]
	v_add_f32_e32 v255, v188, v255
	s_lshl_b32 s46, s46, 14
	s_mov_b32 s101, s46
	v_add_f32_e32 v255, v189, v255
	s_add_i32 s46, s46, s27
	v_add_f32_e32 v255, v208, v255
	s_and_b32 s47, s36, 0xc000
	v_add_f32_e32 v255, v209, v255
	s_add_i32 s47, s47, s31
	v_add_f32_e32 v99, v148, v255
	s_cmpk_gt_u32 s12, 0x80
	s_cselect_b64 s[10:11], -1, 0
	s_and_b64 vcc, exec, s[10:11]
	s_cbranch_vccnz .LBB0_776
	v_lshl_add_u64 v[246:247], s[42:43], 0, v[146:147]
	s_mov_b32 m0, s46
	s_nop 0
	global_load_lds_dwordx4 v[246:247], off
	v_lshl_add_u64 v[246:247], s[44:45], 0, v[142:143]
	s_mov_b32 m0, s47
	s_nop 0
	global_load_lds_dwordx4 v[246:247], off
	v_lshl_add_u64 v[246:247], s[42:43], 0, v[144:145]
	s_add_i32 m0, s46, 0x2000
	s_nop 0
	global_load_lds_dwordx4 v[246:247], off
	v_lshl_add_u64 v[246:247], s[44:45], 0, v[154:155]
	s_add_i32 m0, s47, 0x2000
	s_nop 0
	global_load_lds_dwordx4 v[246:247], off
; __device__ __forceinline__ void partialSM(f32x16& p0, f32x16& p1, float& m_reg, float& mn, float& alpha) {
;   constexpr float C = SCALE * 1.4426950408889634f;
;   float pmax = p0[0]; for (int r = 1; r < 16; ++r) pmax = fmaxf(pmax, p0[r]); for (int r = 0; r < 16; ++r) pmax = fmaxf(pmax, p1[r]);
;   { auto rr = __builtin_amdgcn_permlane32_swap(__float_as_uint(pmax), __float_as_uint(pmax), false, false);
;     pmax = fmaxf(__uint_as_float(rr[0]), __uint_as_float(rr[1])); }
;   if (__builtin_expect(__all(pmax - m_reg <= THR / SCALE), 1)) { mn = m_reg; alpha = 1.f; }
;   else { mn = fmaxf(m_reg, pmax); alpha = __builtin_amdgcn_exp2f((m_reg - mn) * C); m_reg = mn; }
;   float mnC = -mn * C;
;   for (int r = 0; r < 16; ++r) p0[r] = fmaf(p0[r], C, mnC); for (int r = 0; r < 16; ++r) p1[r] = fmaf(p1[r], C, mnC);
;   for (int r = 0; r < 16; ++r) p0[r] = __builtin_amdgcn_exp2f(p0[r]);
; }
; __device__ __forceinline__ void finishSM(f32x16& p0, f32x16& p1, float alpha, float& l_reg, bf16x8& pa0, bf16x8& pa1, bf16x8& pa2, bf16x8& pa3) {
;   for (int r = 0; r < 16; ++r) p1[r] = __builtin_amdgcn_exp2f(p1[r]);
;   float ps = 0; for (int r = 0; r < 16; ++r) ps += p0[r]; for (int r = 0; r < 16; ++r) ps += p1[r];
;   { auto rr = __builtin_amdgcn_permlane32_swap(__float_as_uint(ps), __float_as_uint(ps), false, false);
;     ps = __uint_as_float(rr[0]) + __uint_as_float(rr[1]); }
;   l_reg = l_reg * alpha + ps;
;     ...
;   PK4(p0, 0, pa0); PK4(p0, 8, pa1); PK4(p1, 0, pa2); PK4(p1, 8, pa3);
;     ...
; }
; template <int D0> __device__ __forceinline__ void v_frag_read(VFrag& f, int vb) {
;   f.l0 = tr_read<v_rd_off(D0, 0, 0)>(vb); f.h0 = tr_read<v_rd_off(D0, 0, 1)>(vb); f.l1 = tr_read<v_rd_off(D0, 1, 0)>(vb); f.h1 = tr_read<v_rd_off(D0, 1, 1)>(vb);
;   f.l2 = tr_read<v_rd_off(D0, 2, 0)>(vb); f.h2 = tr_read<v_rd_off(D0, 2, 1)>(vb); f.l3 = tr_read<v_rd_off(D0, 3, 0)>(vb); f.h3 = tr_read<v_rd_off(D0, 3, 1)>(vb);
; }
; __device__ __forceinline__ void pv_mma(f32x16& od, const VFrag& f, bf16x8 pa0, bf16x8 pa1, bf16x8 pa2, bf16x8 pa3) {
;     ...
;   od = __builtin_amdgcn_mfma_f32_32x32x16_bf16(pa0, PK(f.l0, f.h0), od, 0, 0, 0);
;   od = __builtin_amdgcn_mfma_f32_32x32x16_bf16(pa1, PK(f.l1, f.h1), od, 0, 0, 0);
;   od = __builtin_amdgcn_mfma_f32_32x32x16_bf16(pa2, PK(f.l2, f.h2), od, 0, 0, 0);
;   od = __builtin_amdgcn_mfma_f32_32x32x16_bf16(pa3, PK(f.l3, f.h3), od, 0, 0, 0);
;     ...
; }
.LBB0_776:
	v_mov_b32_e32 v100, v99
	s_nop 1
	v_permlane32_swap_b32_e32 v99, v100
	v_cvt_pk_bf16_f32 v102, v192, v193
	v_cvt_pk_bf16_f32 v103, v194, v195
	v_cvt_pk_bf16_f32 v104, v196, v197
	v_cvt_pk_bf16_f32 v105, v198, v199
	s_waitcnt lgkmcnt(8)
	v_mfma_f32_32x32x16_bf16 v[66:81], v[174:177], v[114:117], v[66:81]
	v_cvt_pk_bf16_f32 v106, v200, v201
	v_cvt_pk_bf16_f32 v107, v202, v203
	v_cvt_pk_bf16_f32 v108, v204, v205
	v_cvt_pk_bf16_f32 v109, v206, v207
	v_cvt_pk_bf16_f32 v110, v210, v211
	v_cvt_pk_bf16_f32 v111, v212, v213
	v_cvt_pk_bf16_f32 v112, v214, v215
	v_cvt_pk_bf16_f32 v113, v149, v150
	v_cvt_pk_bf16_f32 v134, v151, v186
	v_cvt_pk_bf16_f32 v135, v187, v188
	v_cvt_pk_bf16_f32 v136, v189, v208
	v_cvt_pk_bf16_f32 v137, v209, v148
	v_permlane32_swap_b32_e32 v102, v104
	v_permlane32_swap_b32_e32 v103, v105
	v_permlane32_swap_b32_e32 v106, v108
	v_permlane32_swap_b32_e32 v107, v109
	v_permlane32_swap_b32_e32 v110, v112
	v_permlane32_swap_b32_e32 v111, v113
	v_permlane32_swap_b32_e32 v134, v136
	v_permlane32_swap_b32_e32 v135, v137
	ds_read_b64_tr_b16 v[204:205], v244 offset:0x200
	ds_read_b64_tr_b16 v[206:207], v244 offset:0xa00
	ds_read_b64_tr_b16 v[208:209], v244 offset:0x1200
	ds_read_b64_tr_b16 v[210:211], v244 offset:0x1a00
	ds_read_b64_tr_b16 v[212:213], v244 offset:0x2200
	ds_read_b64_tr_b16 v[214:215], v244 offset:0x2a00
	ds_read_b64_tr_b16 v[216:217], v244 offset:0x3200
	ds_read_b64_tr_b16 v[218:219], v244 offset:0x3a00
	s_waitcnt lgkmcnt(14)
	v_mfma_f32_32x32x16_bf16 v[18:33], v[102:105], v[228:231], v[18:33]
	v_max_f32_e32 v245, v83, v83
	v_max_f32_e32 v246, v82, v82
	v_max_f32_e32 v245, v246, v245
	v_max3_f32 v245, v245, v84, v85
	v_max3_f32 v245, v245, v86, v87
	v_max3_f32 v245, v245, v88, v89
	v_max3_f32 v245, v245, v90, v91
	v_max3_f32 v245, v245, v92, v93
	s_waitcnt lgkmcnt(12)
	v_mfma_f32_32x32x16_bf16 v[18:33], v[106:109], v[232:235], v[18:33]
	v_max3_f32 v245, v245, v94, v95
	v_max3_f32 v245, v245, v96, v97
	v_max3_f32 v245, v245, v66, v67
	v_max3_f32 v245, v245, v68, v69
	v_max3_f32 v245, v245, v70, v71
	v_max3_f32 v245, v245, v72, v73
	v_max3_f32 v245, v245, v74, v75
	v_max3_f32 v245, v245, v76, v77
	s_waitcnt lgkmcnt(10)
	v_mfma_f32_32x32x16_bf16 v[18:33], v[110:113], v[236:239], v[18:33]
	v_max3_f32 v245, v245, v78, v79
	v_max3_f32 v245, v245, v80, v81
	v_mov_b32_e32 v246, v245
	s_nop 1
	v_permlane32_swap_b32_e32 v245, v246
	v_max_f32_e32 v246, v246, v246
	v_max_f32_e32 v245, v245, v245
	v_max_f32_e32 v245, v245, v246
	v_sub_f32_e32 v246, v245, v133
	s_waitcnt lgkmcnt(8)
	v_mfma_f32_32x32x16_bf16 v[18:33], v[134:137], v[240:243], v[18:33]
	v_cmp_ge_f32_e32 vcc, s63, v246
	v_max_f32_e32 v246, v133, v133
	v_max_f32_e32 v245, v246, v245
	v_sub_f32_e32 v246, v133, v245
	v_mul_f32_e32 v246, 0x3e38aa3b, v246
	v_exp_f32_e32 v246, v246
	s_cmp_eq_u64 vcc, exec
	s_cselect_b64 s[0:1], -1, 0
	v_cndmask_b32_e64 v247, v246, 1.0, s[0:1]
	ds_read_b64_tr_b16 v[228:229], v244 offset:0x400
	ds_read_b64_tr_b16 v[230:231], v244 offset:0xc00
	ds_read_b64_tr_b16 v[232:233], v244 offset:0x1400
	ds_read_b64_tr_b16 v[234:235], v244 offset:0x1c00
	ds_read_b64_tr_b16 v[236:237], v244 offset:0x2400
	ds_read_b64_tr_b16 v[238:239], v244 offset:0x2c00
	ds_read_b64_tr_b16 v[240:241], v244 offset:0x3400
	ds_read_b64_tr_b16 v[242:243], v244 offset:0x3c00
	v_cndmask_b32_e64 v174, v245, v133, s[0:1]
	v_mul_f32_e32 v98, 0xbe38aa3b, v174
	s_waitcnt lgkmcnt(14)
	v_mfma_f32_32x32x16_bf16 v[50:65], v[102:105], v[204:207], v[50:65]
	v_fmamk_f32 v82, v82, 0x3e38aa3b, v98
	v_fmamk_f32 v83, v83, 0x3e38aa3b, v98
	v_fmamk_f32 v84, v84, 0x3e38aa3b, v98
	v_fmamk_f32 v85, v85, 0x3e38aa3b, v98
	s_waitcnt lgkmcnt(12)
	v_mfma_f32_32x32x16_bf16 v[50:65], v[106:109], v[208:211], v[50:65]
	v_fmamk_f32 v86, v86, 0x3e38aa3b, v98
	v_fmamk_f32 v87, v87, 0x3e38aa3b, v98
	v_fmamk_f32 v88, v88, 0x3e38aa3b, v98
	v_fmamk_f32 v89, v89, 0x3e38aa3b, v98
	s_waitcnt lgkmcnt(10)
	v_mfma_f32_32x32x16_bf16 v[50:65], v[110:113], v[212:215], v[50:65]
	v_fmamk_f32 v90, v90, 0x3e38aa3b, v98
	v_fmamk_f32 v91, v91, 0x3e38aa3b, v98
	v_fmamk_f32 v92, v92, 0x3e38aa3b, v98
	v_fmamk_f32 v93, v93, 0x3e38aa3b, v98
	s_waitcnt lgkmcnt(8)
	v_mfma_f32_32x32x16_bf16 v[50:65], v[134:137], v[216:219], v[50:65]
	v_fmamk_f32 v94, v94, 0x3e38aa3b, v98
	v_fmamk_f32 v95, v95, 0x3e38aa3b, v98
	v_fmamk_f32 v96, v96, 0x3e38aa3b, v98
	v_fmamk_f32 v97, v97, 0x3e38aa3b, v98
	ds_read_b64_tr_b16 v[204:205], v244 offset:0x600
	ds_read_b64_tr_b16 v[206:207], v244 offset:0xe00
	ds_read_b64_tr_b16 v[208:209], v244 offset:0x1600
	ds_read_b64_tr_b16 v[210:211], v244 offset:0x1e00
	ds_read_b64_tr_b16 v[212:213], v244 offset:0x2600
	ds_read_b64_tr_b16 v[214:215], v244 offset:0x2e00
	ds_read_b64_tr_b16 v[216:217], v244 offset:0x3600
	ds_read_b64_tr_b16 v[218:219], v244 offset:0x3e00
	s_waitcnt lgkmcnt(14)
	v_mfma_f32_32x32x16_bf16 v[34:49], v[102:105], v[228:231], v[34:49]
	s_mov_b32 s46, 0x3e38aa3b
	v_pk_fma_f32 v[80:81], v[80:81], s[46:47], v[98:99] op_sel_hi:[1,0,0]
	v_pk_fma_f32 v[78:79], v[78:79], s[46:47], v[98:99] op_sel_hi:[1,0,0]
	s_waitcnt lgkmcnt(12)
	v_mfma_f32_32x32x16_bf16 v[34:49], v[106:109], v[232:235], v[34:49]
	v_pk_fma_f32 v[76:77], v[76:77], s[46:47], v[98:99] op_sel_hi:[1,0,0]
	v_pk_fma_f32 v[74:75], v[74:75], s[46:47], v[98:99] op_sel_hi:[1,0,0]
	v_pk_fma_f32 v[72:73], v[72:73], s[46:47], v[98:99] op_sel_hi:[1,0,0]
	s_waitcnt lgkmcnt(10)
	v_mfma_f32_32x32x16_bf16 v[34:49], v[110:113], v[236:239], v[34:49]
	v_pk_fma_f32 v[70:71], v[70:71], s[46:47], v[98:99] op_sel_hi:[1,0,0]
	v_pk_fma_f32 v[68:69], v[68:69], s[46:47], v[98:99] op_sel_hi:[1,0,0]
	v_pk_fma_f32 v[66:67], v[66:67], s[46:47], v[98:99] op_sel_hi:[1,0,0]
	s_waitcnt lgkmcnt(8)
	v_mfma_f32_32x32x16_bf16 v[34:49], v[134:137], v[240:243], v[34:49]
	v_exp_f32_e32 v175, v82
	v_exp_f32_e32 v177, v83
	v_exp_f32_e32 v192, v84
	s_waitcnt lgkmcnt(6)
	v_mfma_f32_32x32x16_bf16 v[2:17], v[102:105], v[204:207], v[2:17]
	v_mov_b32_e32 v205, v247
	v_exp_f32_e32 v204, v97
	v_exp_f32_e32 v195, v85
	v_exp_f32_e32 v196, v86
	v_exp_f32_e32 v199, v87
	v_exp_f32_e32 v200, v88
	s_waitcnt lgkmcnt(4)
	v_mfma_f32_32x32x16_bf16 v[2:17], v[106:109], v[208:211], v[2:17]
	v_exp_f32_e32 v203, v89
	v_exp_f32_e32 v176, v90
	v_exp_f32_e32 v193, v91
	v_exp_f32_e32 v194, v92
	s_waitcnt lgkmcnt(2)
	v_mfma_f32_32x32x16_bf16 v[2:17], v[110:113], v[212:215], v[2:17]
	v_exp_f32_e32 v197, v93
	v_exp_f32_e32 v198, v94
	v_exp_f32_e32 v201, v95
	v_exp_f32_e32 v202, v96
	s_waitcnt lgkmcnt(0)
	v_mfma_f32_32x32x16_bf16 v[2:17], v[134:137], v[216:219], v[2:17]
	v_add_u32_e32 v245, s100, v169
	v_add_u32_e32 v246, s100, v170
	v_add_u32_e32 v247, s100, v171
	v_add_u32_e32 v255, s100, v172
	v_cmp_gt_f32_e32 vcc, 1.0, v205
	s_cbranch_vccz .LBB0_780
	s_and_saveexec_b64 s[12:13], s[40:41]
	ds_write_b32 v162, v205 offset:128
	s_or_b64 exec, exec, s[12:13]
	s_waitcnt lgkmcnt(0)
	v_add_u32_e32 v101, s18, v140
	ds_read_b128 v[102:105], v101 offset:224
	ds_read_b128 v[106:109], v101 offset:192
	ds_read_b128 v[110:113], v101 offset:160
	ds_read_b128 v[134:137], v101 offset:128
	s_waitcnt lgkmcnt(0)
	v_pk_mul_f32 v[30:31], v[30:31], v[102:103]
	v_pk_mul_f32 v[26:27], v[26:27], v[106:107]
	v_pk_mul_f32 v[22:23], v[22:23], v[110:111]
	v_pk_mul_f32 v[32:33], v[32:33], v[104:105]
	v_pk_mul_f32 v[28:29], v[28:29], v[108:109]
	v_pk_mul_f32 v[24:25], v[24:25], v[112:113]
	v_pk_mul_f32 v[20:21], v[20:21], v[136:137]
	v_pk_mul_f32 v[18:19], v[18:19], v[134:135]
	v_pk_mul_f32 v[62:63], v[62:63], v[102:103]
	v_pk_mul_f32 v[58:59], v[58:59], v[106:107]
	v_pk_mul_f32 v[54:55], v[54:55], v[110:111]
	v_pk_mul_f32 v[64:65], v[64:65], v[104:105]
	v_pk_mul_f32 v[60:61], v[60:61], v[108:109]
	v_pk_mul_f32 v[56:57], v[56:57], v[112:113]
	v_pk_mul_f32 v[52:53], v[52:53], v[136:137]
	v_pk_mul_f32 v[50:51], v[50:51], v[134:135]
	v_pk_mul_f32 v[46:47], v[46:47], v[102:103]
	v_pk_mul_f32 v[42:43], v[42:43], v[106:107]
	v_pk_mul_f32 v[38:39], v[38:39], v[110:111]
	v_pk_mul_f32 v[48:49], v[48:49], v[104:105]
	v_pk_mul_f32 v[44:45], v[44:45], v[108:109]
	v_pk_mul_f32 v[40:41], v[40:41], v[112:113]
	v_pk_mul_f32 v[36:37], v[36:37], v[136:137]
	v_pk_mul_f32 v[34:35], v[34:35], v[134:135]
	v_pk_mul_f32 v[14:15], v[14:15], v[102:103]
	v_pk_mul_f32 v[10:11], v[10:11], v[106:107]
	v_pk_mul_f32 v[6:7], v[6:7], v[110:111]
	v_pk_mul_f32 v[16:17], v[16:17], v[104:105]
	v_pk_mul_f32 v[12:13], v[12:13], v[108:109]
	v_pk_mul_f32 v[8:9], v[8:9], v[112:113]
	v_pk_mul_f32 v[4:5], v[4:5], v[136:137]
	v_pk_mul_f32 v[2:3], v[2:3], v[134:135]

; __global__ void __launch_bounds__(NWAVES * 64, 2) mk_fwd(Args args) {
;     extern __shared__ __attribute__((aligned(16))) unsigned char lds[];
	.amdhsa_kernel _Z6mk_fwd4Args
		.amdhsa_group_segment_fixed_size 0
		.amdhsa_private_segment_fixed_size 0
		.amdhsa_kernarg_size 432
		.amdhsa_user_sgpr_count 2
		.amdhsa_user_sgpr_dispatch_ptr 0
		.amdhsa_user_sgpr_queue_ptr 0
		.amdhsa_user_sgpr_kernarg_segment_ptr 1
		.amdhsa_user_sgpr_dispatch_id 0
		.amdhsa_user_sgpr_kernarg_preload_length 0
		.amdhsa_user_sgpr_kernarg_preload_offset 0
		.amdhsa_user_sgpr_private_segment_size 0
		.amdhsa_uses_dynamic_stack 0
		.amdhsa_enable_private_segment 0
		.amdhsa_system_sgpr_workgroup_id_x 1
		.amdhsa_system_sgpr_workgroup_id_y 0
		.amdhsa_system_sgpr_workgroup_id_z 0
		.amdhsa_system_sgpr_workgroup_info 0
		.amdhsa_system_vgpr_workitem_id 0
		.amdhsa_next_free_vgpr 256
		.amdhsa_next_free_sgpr 102
		.amdhsa_accum_offset 256
		.amdhsa_reserve_vcc 1
		.amdhsa_float_round_mode_32 0
		.amdhsa_float_round_mode_16_64 0
		.amdhsa_float_denorm_mode_32 3
		.amdhsa_float_denorm_mode_16_64 3
		.amdhsa_dx10_clamp 1
		.amdhsa_ieee_mode 1
		.amdhsa_fp16_overflow 0
		.amdhsa_tg_split 0
		.amdhsa_exception_fp_ieee_invalid_op 0
		.amdhsa_exception_fp_denorm_src 0
		.amdhsa_exception_fp_ieee_div_zero 0
		.amdhsa_exception_fp_ieee_overflow 0
		.amdhsa_exception_fp_ieee_underflow 0
		.amdhsa_exception_fp_ieee_inexact 0
		.amdhsa_exception_int_div_zero 0
	.end_amdhsa_kernel

; __global__ void __launch_bounds__(NWAVES * 64, 2) mk_fwd(Args args) {
;     extern __shared__ __attribute__((aligned(16))) unsigned char lds[];
amdhsa.kernels:
  - .agpr_count:     0
    .args:
      - .offset:         0
        .size:           176
        .value_kind:     by_value
      - .offset:         176
        .size:           4
        .value_kind:     hidden_block_count_x
      - .offset:         180
        .size:           4
        .value_kind:     hidden_block_count_y
      - .offset:         184
        .size:           4
        .value_kind:     hidden_block_count_z
      - .offset:         188
        .size:           2
        .value_kind:     hidden_group_size_x
      - .offset:         190
        .size:           2
        .value_kind:     hidden_group_size_y
      - .offset:         192
        .size:           2
        .value_kind:     hidden_group_size_z
      - .offset:         194
        .size:           2
        .value_kind:     hidden_remainder_x
      - .offset:         196
        .size:           2
        .value_kind:     hidden_remainder_y
      - .offset:         198
        .size:           2
        .value_kind:     hidden_remainder_z
      - .offset:         216
        .size:           8
        .value_kind:     hidden_global_offset_x
      - .offset:         224
        .size:           8
        .value_kind:     hidden_global_offset_y
      - .offset:         232
        .size:           8
        .value_kind:     hidden_global_offset_z
      - .offset:         240
        .size:           2
        .value_kind:     hidden_grid_dims
      - .offset:         296
        .size:           4
        .value_kind:     hidden_dynamic_lds_size
    .group_segment_fixed_size: 0
    .kernarg_segment_align: 8
    .kernarg_segment_size: 432
    .language:       OpenCL C
    .language_version:
      - 2
      - 0
    .max_flat_workgroup_size: 512
    .name:           _Z6mk_fwd4Args
    .private_segment_fixed_size: 0
    .sgpr_count:     108
    .sgpr_spill_count: 431
    .symbol:         _Z6mk_fwd4Args.kd
    .uniform_work_group_size: 1
    .uses_dynamic_stack: false
    .vgpr_count:     256
    .vgpr_spill_count: 0
    .wavefront_size: 64
